# phase9 final-norm loop hand-written: 3-deep row prefetch, g hoisted, DPP reduce
# speedup vs baseline: 1.0013x; 1.0013x over previous
.LBB0_1451:
	s_cmp_lt_i32 s22, 10
	s_cselect_b64 s[0:1], -1, 0
	s_cmp_gt_i32 s23, 9
	s_cselect_b64 s[2:3], -1, 0
	s_and_b64 s[0:1], s[0:1], s[2:3]
	s_andn2_b64 vcc, exec, s[0:1]
	s_cbranch_vccnz .LBB0_1477
	s_mov_b64 s[4:5], exec
	s_waitcnt vmcnt(0) lgkmcnt(0)
	v_readfirstlane_b32 s16, v209
	s_lshl_b32 s14, s96, 3
	s_add_u32 s14, s14, s16
	s_lshl_b32 s15, s82, 3
	s_cmp_ge_u32 s14, 0x8000
	s_cbranch_scc1 .LBB0_1465
	v_and_b32_e32 v142, 63, v208
	v_lshlrev_b32_e32 v143, 3, v142
	v_lshlrev_b32_e32 v142, 4, v142
	global_load_dwordx4 v[112:115], v142, s[42:43] offset:0
	global_load_dwordx4 v[116:119], v142, s[42:43] offset:1024
	global_load_dwordx4 v[120:123], v142, s[42:43] offset:2048
	global_load_dwordx4 v[124:127], v142, s[42:43] offset:3072
	v_mov_b32_e32 v140, 0x3a800000
	v_mov_b32_e32 v141, 0x358637bd
	s_lshl_b32 s16, s14, 12
	s_add_u32 s0, s36, s16
	s_addc_u32 s1, s37, 0
	s_add_u32 s8, s18, s16
	s_addc_u32 s9, s19, 0
	s_lshl_b32 s16, s14, 11
	s_add_u32 s2, s20, s16
	s_addc_u32 s3, s21, 0
	s_add_u32 s2, s2, 0x15f60000
	s_addc_u32 s3, s3, 0
	s_add_u32 s6, s20, s16
	s_addc_u32 s7, s21, 0
	s_add_u32 s6, s6, 0x4f60000
	s_addc_u32 s7, s7, 0
	s_lshl_b32 s10, s15, 12
	s_lshl_b32 s12, s15, 11
	global_load_dwordx4 v[16:19], v142, s[0:1]
	global_load_dwordx4 v[20:23], v142, s[0:1] offset:1024
	global_load_dwordx4 v[24:27], v142, s[0:1] offset:2048
	global_load_dwordx4 v[28:31], v142, s[0:1] offset:3072
	global_load_dwordx2 v[32:33], v143, s[2:3]
	global_load_dwordx2 v[34:35], v143, s[2:3] offset:512
	global_load_dwordx2 v[36:37], v143, s[2:3] offset:1024
	global_load_dwordx2 v[38:39], v143, s[2:3] offset:1536
	global_load_dwordx2 v[40:41], v143, s[6:7]
	global_load_dwordx2 v[42:43], v143, s[6:7] offset:512
	global_load_dwordx2 v[44:45], v143, s[6:7] offset:1024
	global_load_dwordx2 v[46:47], v143, s[6:7] offset:1536
	s_add_u32 s0, s0, s10
	s_addc_u32 s1, s1, 0
	s_add_u32 s2, s2, s12
	s_addc_u32 s3, s3, 0
	s_add_u32 s6, s6, s12
	s_addc_u32 s7, s7, 0
	s_add_u32 s14, s14, s15
	s_cmp_ge_u32 s14, 0x8000
	s_cbranch_scc0 .Lfnorm_two
	s_waitcnt vmcnt(0)
	v_lshlrev_b32_e32 v128, 16, v32
	v_and_b32_e32 v129, 0xffff0000, v32
	v_lshlrev_b32_e32 v130, 16, v33
	v_and_b32_e32 v131, 0xffff0000, v33
	v_pk_add_f32 v[16:17], v[16:17], v[128:129]
	v_pk_add_f32 v[18:19], v[18:19], v[130:131]
	v_lshlrev_b32_e32 v132, 16, v34
	v_and_b32_e32 v133, 0xffff0000, v34
	v_lshlrev_b32_e32 v134, 16, v35
	v_and_b32_e32 v135, 0xffff0000, v35
	v_pk_add_f32 v[20:21], v[20:21], v[132:133]
	v_pk_add_f32 v[22:23], v[22:23], v[134:135]
	v_lshlrev_b32_e32 v128, 16, v36
	v_and_b32_e32 v129, 0xffff0000, v36
	v_lshlrev_b32_e32 v130, 16, v37
	v_and_b32_e32 v131, 0xffff0000, v37
	v_pk_add_f32 v[24:25], v[24:25], v[128:129]
	v_pk_add_f32 v[26:27], v[26:27], v[130:131]
	v_lshlrev_b32_e32 v132, 16, v38
	v_and_b32_e32 v133, 0xffff0000, v38
	v_lshlrev_b32_e32 v134, 16, v39
	v_and_b32_e32 v135, 0xffff0000, v39
	v_pk_add_f32 v[28:29], v[28:29], v[132:133]
	v_pk_add_f32 v[30:31], v[30:31], v[134:135]
	v_lshlrev_b32_e32 v128, 16, v40
	v_and_b32_e32 v129, 0xffff0000, v40
	v_lshlrev_b32_e32 v130, 16, v41
	v_and_b32_e32 v131, 0xffff0000, v41
	v_pk_add_f32 v[16:17], v[16:17], v[128:129]
	v_pk_add_f32 v[18:19], v[18:19], v[130:131]
	v_lshlrev_b32_e32 v132, 16, v42
	v_and_b32_e32 v133, 0xffff0000, v42
	v_lshlrev_b32_e32 v134, 16, v43
	v_and_b32_e32 v135, 0xffff0000, v43
	v_pk_add_f32 v[20:21], v[20:21], v[132:133]
	v_pk_add_f32 v[22:23], v[22:23], v[134:135]
	v_lshlrev_b32_e32 v128, 16, v44
	v_and_b32_e32 v129, 0xffff0000, v44
	v_lshlrev_b32_e32 v130, 16, v45
	v_and_b32_e32 v131, 0xffff0000, v45
	v_pk_add_f32 v[24:25], v[24:25], v[128:129]
	v_pk_add_f32 v[26:27], v[26:27], v[130:131]
	v_lshlrev_b32_e32 v132, 16, v46
	v_and_b32_e32 v133, 0xffff0000, v46
	v_lshlrev_b32_e32 v134, 16, v47
	v_and_b32_e32 v135, 0xffff0000, v47
	v_pk_add_f32 v[28:29], v[28:29], v[132:133]
	v_pk_add_f32 v[30:31], v[30:31], v[134:135]
	v_pk_mul_f32 v[136:137], v[16:17], v[16:17]
	v_pk_mul_f32 v[128:129], v[18:19], v[18:19]
	v_pk_fma_f32 v[136:137], v[20:21], v[20:21], v[136:137]
	v_pk_fma_f32 v[128:129], v[22:23], v[22:23], v[128:129]
	v_pk_fma_f32 v[136:137], v[24:25], v[24:25], v[136:137]
	v_pk_fma_f32 v[128:129], v[26:27], v[26:27], v[128:129]
	v_pk_fma_f32 v[136:137], v[28:29], v[28:29], v[136:137]
	v_pk_fma_f32 v[128:129], v[30:31], v[30:31], v[128:129]
	v_pk_add_f32 v[136:137], v[136:137], v[128:129]
	s_nop 0
	v_add_f32_e32 v136, v136, v137
	s_nop 1
	v_add_f32_dpp v136, v136, v136 quad_perm:[1,0,3,2] row_mask:0xf bank_mask:0xf
	s_nop 1
	v_add_f32_dpp v136, v136, v136 quad_perm:[2,3,0,1] row_mask:0xf bank_mask:0xf
	s_nop 1
	v_add_f32_dpp v136, v136, v136 row_half_mirror row_mask:0xf bank_mask:0xf
	s_nop 1
	v_add_f32_dpp v136, v136, v136 row_mirror row_mask:0xf bank_mask:0xf
	s_nop 1
	v_add_f32_dpp v136, v136, v136 row_bcast:15 row_mask:0xa bank_mask:0xf
	s_nop 1
	v_add_f32_dpp v136, v136, v136 row_bcast:31 row_mask:0xc bank_mask:0xf
	s_nop 1
	v_readlane_b32 s16, v136, 63
	s_nop 3
	v_fma_f32 v138, s16, v140, v141
	v_rsq_f32_e32 v138, v138
	s_nop 0
	v_mov_b32_e32 v139, v138
	v_pk_mul_f32 v[16:17], v[16:17], v[138:139]
	v_pk_mul_f32 v[18:19], v[18:19], v[138:139]
	v_pk_mul_f32 v[20:21], v[20:21], v[138:139]
	v_pk_mul_f32 v[22:23], v[22:23], v[138:139]
	v_pk_mul_f32 v[24:25], v[24:25], v[138:139]
	v_pk_mul_f32 v[26:27], v[26:27], v[138:139]
	v_pk_mul_f32 v[28:29], v[28:29], v[138:139]
	v_pk_mul_f32 v[30:31], v[30:31], v[138:139]
	v_pk_mul_f32 v[16:17], v[16:17], v[112:113]
	v_pk_mul_f32 v[18:19], v[18:19], v[114:115]
	v_pk_mul_f32 v[20:21], v[20:21], v[116:117]
	v_pk_mul_f32 v[22:23], v[22:23], v[118:119]
	v_pk_mul_f32 v[24:25], v[24:25], v[120:121]
	v_pk_mul_f32 v[26:27], v[26:27], v[122:123]
	v_pk_mul_f32 v[28:29], v[28:29], v[124:125]
	v_pk_mul_f32 v[30:31], v[30:31], v[126:127]
	global_store_dwordx4 v142, v[16:19], s[8:9]
	global_store_dwordx4 v142, v[20:23], s[8:9] offset:1024
	global_store_dwordx4 v142, v[24:27], s[8:9] offset:2048
	global_store_dwordx4 v142, v[28:31], s[8:9] offset:3072
	s_add_u32 s8, s8, s10
	s_addc_u32 s9, s9, 0
	s_branch .Lfnorm_done
.Lfnorm_two:
	global_load_dwordx4 v[48:51], v142, s[0:1]
	global_load_dwordx4 v[52:55], v142, s[0:1] offset:1024
	global_load_dwordx4 v[56:59], v142, s[0:1] offset:2048
	global_load_dwordx4 v[60:63], v142, s[0:1] offset:3072
	global_load_dwordx2 v[64:65], v143, s[2:3]
	global_load_dwordx2 v[66:67], v143, s[2:3] offset:512
	global_load_dwordx2 v[68:69], v143, s[2:3] offset:1024
	global_load_dwordx2 v[70:71], v143, s[2:3] offset:1536
	global_load_dwordx2 v[72:73], v143, s[6:7]
	global_load_dwordx2 v[74:75], v143, s[6:7] offset:512
	global_load_dwordx2 v[76:77], v143, s[6:7] offset:1024
	global_load_dwordx2 v[78:79], v143, s[6:7] offset:1536
	s_add_u32 s0, s0, s10
	s_addc_u32 s1, s1, 0
	s_add_u32 s2, s2, s12
	s_addc_u32 s3, s3, 0
	s_add_u32 s6, s6, s12
	s_addc_u32 s7, s7, 0
	s_add_u32 s14, s14, s15
.Lfnorm_loop:
	s_cmp_ge_u32 s14, 0x8000
	s_cbranch_scc1 .Lfnorm_drain0
	global_load_dwordx4 v[80:83], v142, s[0:1]
	global_load_dwordx4 v[84:87], v142, s[0:1] offset:1024
	global_load_dwordx4 v[88:91], v142, s[0:1] offset:2048
	global_load_dwordx4 v[92:95], v142, s[0:1] offset:3072
	global_load_dwordx2 v[96:97], v143, s[2:3]
	global_load_dwordx2 v[98:99], v143, s[2:3] offset:512
	global_load_dwordx2 v[100:101], v143, s[2:3] offset:1024
	global_load_dwordx2 v[102:103], v143, s[2:3] offset:1536
	global_load_dwordx2 v[104:105], v143, s[6:7]
	global_load_dwordx2 v[106:107], v143, s[6:7] offset:512
	global_load_dwordx2 v[108:109], v143, s[6:7] offset:1024
	global_load_dwordx2 v[110:111], v143, s[6:7] offset:1536
	s_add_u32 s0, s0, s10
	s_addc_u32 s1, s1, 0
	s_add_u32 s2, s2, s12
	s_addc_u32 s3, s3, 0
	s_add_u32 s6, s6, s12
	s_addc_u32 s7, s7, 0
	s_add_u32 s14, s14, s15
	s_waitcnt vmcnt(24)
	v_lshlrev_b32_e32 v128, 16, v32
	v_and_b32_e32 v129, 0xffff0000, v32
	v_lshlrev_b32_e32 v130, 16, v33
	v_and_b32_e32 v131, 0xffff0000, v33
	v_pk_add_f32 v[16:17], v[16:17], v[128:129]
	v_pk_add_f32 v[18:19], v[18:19], v[130:131]
	v_lshlrev_b32_e32 v132, 16, v34
	v_and_b32_e32 v133, 0xffff0000, v34
	v_lshlrev_b32_e32 v134, 16, v35
	v_and_b32_e32 v135, 0xffff0000, v35
	v_pk_add_f32 v[20:21], v[20:21], v[132:133]
	v_pk_add_f32 v[22:23], v[22:23], v[134:135]
	v_lshlrev_b32_e32 v128, 16, v36
	v_and_b32_e32 v129, 0xffff0000, v36
	v_lshlrev_b32_e32 v130, 16, v37
	v_and_b32_e32 v131, 0xffff0000, v37
	v_pk_add_f32 v[24:25], v[24:25], v[128:129]
	v_pk_add_f32 v[26:27], v[26:27], v[130:131]
	v_lshlrev_b32_e32 v132, 16, v38
	v_and_b32_e32 v133, 0xffff0000, v38
	v_lshlrev_b32_e32 v134, 16, v39
	v_and_b32_e32 v135, 0xffff0000, v39
	v_pk_add_f32 v[28:29], v[28:29], v[132:133]
	v_pk_add_f32 v[30:31], v[30:31], v[134:135]
	v_lshlrev_b32_e32 v128, 16, v40
	v_and_b32_e32 v129, 0xffff0000, v40
	v_lshlrev_b32_e32 v130, 16, v41
	v_and_b32_e32 v131, 0xffff0000, v41
	v_pk_add_f32 v[16:17], v[16:17], v[128:129]
	v_pk_add_f32 v[18:19], v[18:19], v[130:131]
	v_lshlrev_b32_e32 v132, 16, v42
	v_and_b32_e32 v133, 0xffff0000, v42
	v_lshlrev_b32_e32 v134, 16, v43
	v_and_b32_e32 v135, 0xffff0000, v43
	v_pk_add_f32 v[20:21], v[20:21], v[132:133]
	v_pk_add_f32 v[22:23], v[22:23], v[134:135]
	v_lshlrev_b32_e32 v128, 16, v44
	v_and_b32_e32 v129, 0xffff0000, v44
	v_lshlrev_b32_e32 v130, 16, v45
	v_and_b32_e32 v131, 0xffff0000, v45
	v_pk_add_f32 v[24:25], v[24:25], v[128:129]
	v_pk_add_f32 v[26:27], v[26:27], v[130:131]
	v_lshlrev_b32_e32 v132, 16, v46
	v_and_b32_e32 v133, 0xffff0000, v46
	v_lshlrev_b32_e32 v134, 16, v47
	v_and_b32_e32 v135, 0xffff0000, v47
	v_pk_add_f32 v[28:29], v[28:29], v[132:133]
	v_pk_add_f32 v[30:31], v[30:31], v[134:135]
	v_pk_mul_f32 v[136:137], v[16:17], v[16:17]
	v_pk_mul_f32 v[128:129], v[18:19], v[18:19]
	v_pk_fma_f32 v[136:137], v[20:21], v[20:21], v[136:137]
	v_pk_fma_f32 v[128:129], v[22:23], v[22:23], v[128:129]
	v_pk_fma_f32 v[136:137], v[24:25], v[24:25], v[136:137]
	v_pk_fma_f32 v[128:129], v[26:27], v[26:27], v[128:129]
	v_pk_fma_f32 v[136:137], v[28:29], v[28:29], v[136:137]
	v_pk_fma_f32 v[128:129], v[30:31], v[30:31], v[128:129]
	v_pk_add_f32 v[136:137], v[136:137], v[128:129]
	s_nop 0
	v_add_f32_e32 v136, v136, v137
	s_nop 1
	v_add_f32_dpp v136, v136, v136 quad_perm:[1,0,3,2] row_mask:0xf bank_mask:0xf
	s_nop 1
	v_add_f32_dpp v136, v136, v136 quad_perm:[2,3,0,1] row_mask:0xf bank_mask:0xf
	s_nop 1
	v_add_f32_dpp v136, v136, v136 row_half_mirror row_mask:0xf bank_mask:0xf
	s_nop 1
	v_add_f32_dpp v136, v136, v136 row_mirror row_mask:0xf bank_mask:0xf
	s_nop 1
	v_add_f32_dpp v136, v136, v136 row_bcast:15 row_mask:0xa bank_mask:0xf
	s_nop 1
	v_add_f32_dpp v136, v136, v136 row_bcast:31 row_mask:0xc bank_mask:0xf
	s_nop 1
	v_readlane_b32 s16, v136, 63
	s_nop 3
	v_fma_f32 v138, s16, v140, v141
	v_rsq_f32_e32 v138, v138
	s_nop 0
	v_mov_b32_e32 v139, v138
	v_pk_mul_f32 v[16:17], v[16:17], v[138:139]
	v_pk_mul_f32 v[18:19], v[18:19], v[138:139]
	v_pk_mul_f32 v[20:21], v[20:21], v[138:139]
	v_pk_mul_f32 v[22:23], v[22:23], v[138:139]
	v_pk_mul_f32 v[24:25], v[24:25], v[138:139]
	v_pk_mul_f32 v[26:27], v[26:27], v[138:139]
	v_pk_mul_f32 v[28:29], v[28:29], v[138:139]
	v_pk_mul_f32 v[30:31], v[30:31], v[138:139]
	v_pk_mul_f32 v[16:17], v[16:17], v[112:113]
	v_pk_mul_f32 v[18:19], v[18:19], v[114:115]
	v_pk_mul_f32 v[20:21], v[20:21], v[116:117]
	v_pk_mul_f32 v[22:23], v[22:23], v[118:119]
	v_pk_mul_f32 v[24:25], v[24:25], v[120:121]
	v_pk_mul_f32 v[26:27], v[26:27], v[122:123]
	v_pk_mul_f32 v[28:29], v[28:29], v[124:125]
	v_pk_mul_f32 v[30:31], v[30:31], v[126:127]
	global_store_dwordx4 v142, v[16:19], s[8:9]
	global_store_dwordx4 v142, v[20:23], s[8:9] offset:1024
	global_store_dwordx4 v142, v[24:27], s[8:9] offset:2048
	global_store_dwordx4 v142, v[28:31], s[8:9] offset:3072
	s_add_u32 s8, s8, s10
	s_addc_u32 s9, s9, 0
	s_cmp_ge_u32 s14, 0x8000
	s_cbranch_scc1 .Lfnorm_drain1
	global_load_dwordx4 v[16:19], v142, s[0:1]
	global_load_dwordx4 v[20:23], v142, s[0:1] offset:1024
	global_load_dwordx4 v[24:27], v142, s[0:1] offset:2048
	global_load_dwordx4 v[28:31], v142, s[0:1] offset:3072
	global_load_dwordx2 v[32:33], v143, s[2:3]
	global_load_dwordx2 v[34:35], v143, s[2:3] offset:512
	global_load_dwordx2 v[36:37], v143, s[2:3] offset:1024
	global_load_dwordx2 v[38:39], v143, s[2:3] offset:1536
	global_load_dwordx2 v[40:41], v143, s[6:7]
	global_load_dwordx2 v[42:43], v143, s[6:7] offset:512
	global_load_dwordx2 v[44:45], v143, s[6:7] offset:1024
	global_load_dwordx2 v[46:47], v143, s[6:7] offset:1536
	s_add_u32 s0, s0, s10
	s_addc_u32 s1, s1, 0
	s_add_u32 s2, s2, s12
	s_addc_u32 s3, s3, 0
	s_add_u32 s6, s6, s12
	s_addc_u32 s7, s7, 0
	s_add_u32 s14, s14, s15
	s_waitcnt vmcnt(24)
	v_lshlrev_b32_e32 v128, 16, v64
	v_and_b32_e32 v129, 0xffff0000, v64
	v_lshlrev_b32_e32 v130, 16, v65
	v_and_b32_e32 v131, 0xffff0000, v65
	v_pk_add_f32 v[48:49], v[48:49], v[128:129]
	v_pk_add_f32 v[50:51], v[50:51], v[130:131]
	v_lshlrev_b32_e32 v132, 16, v66
	v_and_b32_e32 v133, 0xffff0000, v66
	v_lshlrev_b32_e32 v134, 16, v67
	v_and_b32_e32 v135, 0xffff0000, v67
	v_pk_add_f32 v[52:53], v[52:53], v[132:133]
	v_pk_add_f32 v[54:55], v[54:55], v[134:135]
	v_lshlrev_b32_e32 v128, 16, v68
	v_and_b32_e32 v129, 0xffff0000, v68
	v_lshlrev_b32_e32 v130, 16, v69
	v_and_b32_e32 v131, 0xffff0000, v69
	v_pk_add_f32 v[56:57], v[56:57], v[128:129]
	v_pk_add_f32 v[58:59], v[58:59], v[130:131]
	v_lshlrev_b32_e32 v132, 16, v70
	v_and_b32_e32 v133, 0xffff0000, v70
	v_lshlrev_b32_e32 v134, 16, v71
	v_and_b32_e32 v135, 0xffff0000, v71
	v_pk_add_f32 v[60:61], v[60:61], v[132:133]
	v_pk_add_f32 v[62:63], v[62:63], v[134:135]
	v_lshlrev_b32_e32 v128, 16, v72
	v_and_b32_e32 v129, 0xffff0000, v72
	v_lshlrev_b32_e32 v130, 16, v73
	v_and_b32_e32 v131, 0xffff0000, v73
	v_pk_add_f32 v[48:49], v[48:49], v[128:129]
	v_pk_add_f32 v[50:51], v[50:51], v[130:131]
	v_lshlrev_b32_e32 v132, 16, v74
	v_and_b32_e32 v133, 0xffff0000, v74
	v_lshlrev_b32_e32 v134, 16, v75
	v_and_b32_e32 v135, 0xffff0000, v75
	v_pk_add_f32 v[52:53], v[52:53], v[132:133]
	v_pk_add_f32 v[54:55], v[54:55], v[134:135]
	v_lshlrev_b32_e32 v128, 16, v76
	v_and_b32_e32 v129, 0xffff0000, v76
	v_lshlrev_b32_e32 v130, 16, v77
	v_and_b32_e32 v131, 0xffff0000, v77
	v_pk_add_f32 v[56:57], v[56:57], v[128:129]
	v_pk_add_f32 v[58:59], v[58:59], v[130:131]
	v_lshlrev_b32_e32 v132, 16, v78
	v_and_b32_e32 v133, 0xffff0000, v78
	v_lshlrev_b32_e32 v134, 16, v79
	v_and_b32_e32 v135, 0xffff0000, v79
	v_pk_add_f32 v[60:61], v[60:61], v[132:133]
	v_pk_add_f32 v[62:63], v[62:63], v[134:135]
	v_pk_mul_f32 v[136:137], v[48:49], v[48:49]
	v_pk_mul_f32 v[128:129], v[50:51], v[50:51]
	v_pk_fma_f32 v[136:137], v[52:53], v[52:53], v[136:137]
	v_pk_fma_f32 v[128:129], v[54:55], v[54:55], v[128:129]
	v_pk_fma_f32 v[136:137], v[56:57], v[56:57], v[136:137]
	v_pk_fma_f32 v[128:129], v[58:59], v[58:59], v[128:129]
	v_pk_fma_f32 v[136:137], v[60:61], v[60:61], v[136:137]
	v_pk_fma_f32 v[128:129], v[62:63], v[62:63], v[128:129]
	v_pk_add_f32 v[136:137], v[136:137], v[128:129]
	s_nop 0
	v_add_f32_e32 v136, v136, v137
	s_nop 1
	v_add_f32_dpp v136, v136, v136 quad_perm:[1,0,3,2] row_mask:0xf bank_mask:0xf
	s_nop 1
	v_add_f32_dpp v136, v136, v136 quad_perm:[2,3,0,1] row_mask:0xf bank_mask:0xf
	s_nop 1
	v_add_f32_dpp v136, v136, v136 row_half_mirror row_mask:0xf bank_mask:0xf
	s_nop 1
	v_add_f32_dpp v136, v136, v136 row_mirror row_mask:0xf bank_mask:0xf
	s_nop 1
	v_add_f32_dpp v136, v136, v136 row_bcast:15 row_mask:0xa bank_mask:0xf
	s_nop 1
	v_add_f32_dpp v136, v136, v136 row_bcast:31 row_mask:0xc bank_mask:0xf
	s_nop 1
	v_readlane_b32 s16, v136, 63
	s_nop 3
	v_fma_f32 v138, s16, v140, v141
	v_rsq_f32_e32 v138, v138
	s_nop 0
	v_mov_b32_e32 v139, v138
	v_pk_mul_f32 v[48:49], v[48:49], v[138:139]
	v_pk_mul_f32 v[50:51], v[50:51], v[138:139]
	v_pk_mul_f32 v[52:53], v[52:53], v[138:139]
	v_pk_mul_f32 v[54:55], v[54:55], v[138:139]
	v_pk_mul_f32 v[56:57], v[56:57], v[138:139]
	v_pk_mul_f32 v[58:59], v[58:59], v[138:139]
	v_pk_mul_f32 v[60:61], v[60:61], v[138:139]
	v_pk_mul_f32 v[62:63], v[62:63], v[138:139]
	v_pk_mul_f32 v[48:49], v[48:49], v[112:113]
	v_pk_mul_f32 v[50:51], v[50:51], v[114:115]
	v_pk_mul_f32 v[52:53], v[52:53], v[116:117]
	v_pk_mul_f32 v[54:55], v[54:55], v[118:119]
	v_pk_mul_f32 v[56:57], v[56:57], v[120:121]
	v_pk_mul_f32 v[58:59], v[58:59], v[122:123]
	v_pk_mul_f32 v[60:61], v[60:61], v[124:125]
	v_pk_mul_f32 v[62:63], v[62:63], v[126:127]
	global_store_dwordx4 v142, v[48:51], s[8:9]
	global_store_dwordx4 v142, v[52:55], s[8:9] offset:1024
	global_store_dwordx4 v142, v[56:59], s[8:9] offset:2048
	global_store_dwordx4 v142, v[60:63], s[8:9] offset:3072
	s_add_u32 s8, s8, s10
	s_addc_u32 s9, s9, 0
	s_cmp_ge_u32 s14, 0x8000
	s_cbranch_scc1 .Lfnorm_drain2
	global_load_dwordx4 v[48:51], v142, s[0:1]
	global_load_dwordx4 v[52:55], v142, s[0:1] offset:1024
	global_load_dwordx4 v[56:59], v142, s[0:1] offset:2048
	global_load_dwordx4 v[60:63], v142, s[0:1] offset:3072
	global_load_dwordx2 v[64:65], v143, s[2:3]
	global_load_dwordx2 v[66:67], v143, s[2:3] offset:512
	global_load_dwordx2 v[68:69], v143, s[2:3] offset:1024
	global_load_dwordx2 v[70:71], v143, s[2:3] offset:1536
	global_load_dwordx2 v[72:73], v143, s[6:7]
	global_load_dwordx2 v[74:75], v143, s[6:7] offset:512
	global_load_dwordx2 v[76:77], v143, s[6:7] offset:1024
	global_load_dwordx2 v[78:79], v143, s[6:7] offset:1536
	s_add_u32 s0, s0, s10
	s_addc_u32 s1, s1, 0
	s_add_u32 s2, s2, s12
	s_addc_u32 s3, s3, 0
	s_add_u32 s6, s6, s12
	s_addc_u32 s7, s7, 0
	s_add_u32 s14, s14, s15
	s_waitcnt vmcnt(24)
	v_lshlrev_b32_e32 v128, 16, v96
	v_and_b32_e32 v129, 0xffff0000, v96
	v_lshlrev_b32_e32 v130, 16, v97
	v_and_b32_e32 v131, 0xffff0000, v97
	v_pk_add_f32 v[80:81], v[80:81], v[128:129]
	v_pk_add_f32 v[82:83], v[82:83], v[130:131]
	v_lshlrev_b32_e32 v132, 16, v98
	v_and_b32_e32 v133, 0xffff0000, v98
	v_lshlrev_b32_e32 v134, 16, v99
	v_and_b32_e32 v135, 0xffff0000, v99
	v_pk_add_f32 v[84:85], v[84:85], v[132:133]
	v_pk_add_f32 v[86:87], v[86:87], v[134:135]
	v_lshlrev_b32_e32 v128, 16, v100
	v_and_b32_e32 v129, 0xffff0000, v100
	v_lshlrev_b32_e32 v130, 16, v101
	v_and_b32_e32 v131, 0xffff0000, v101
	v_pk_add_f32 v[88:89], v[88:89], v[128:129]
	v_pk_add_f32 v[90:91], v[90:91], v[130:131]
	v_lshlrev_b32_e32 v132, 16, v102
	v_and_b32_e32 v133, 0xffff0000, v102
	v_lshlrev_b32_e32 v134, 16, v103
	v_and_b32_e32 v135, 0xffff0000, v103
	v_pk_add_f32 v[92:93], v[92:93], v[132:133]
	v_pk_add_f32 v[94:95], v[94:95], v[134:135]
	v_lshlrev_b32_e32 v128, 16, v104
	v_and_b32_e32 v129, 0xffff0000, v104
	v_lshlrev_b32_e32 v130, 16, v105
	v_and_b32_e32 v131, 0xffff0000, v105
	v_pk_add_f32 v[80:81], v[80:81], v[128:129]
	v_pk_add_f32 v[82:83], v[82:83], v[130:131]
	v_lshlrev_b32_e32 v132, 16, v106
	v_and_b32_e32 v133, 0xffff0000, v106
	v_lshlrev_b32_e32 v134, 16, v107
	v_and_b32_e32 v135, 0xffff0000, v107
	v_pk_add_f32 v[84:85], v[84:85], v[132:133]
	v_pk_add_f32 v[86:87], v[86:87], v[134:135]
	v_lshlrev_b32_e32 v128, 16, v108
	v_and_b32_e32 v129, 0xffff0000, v108
	v_lshlrev_b32_e32 v130, 16, v109
	v_and_b32_e32 v131, 0xffff0000, v109
	v_pk_add_f32 v[88:89], v[88:89], v[128:129]
	v_pk_add_f32 v[90:91], v[90:91], v[130:131]
	v_lshlrev_b32_e32 v132, 16, v110
	v_and_b32_e32 v133, 0xffff0000, v110
	v_lshlrev_b32_e32 v134, 16, v111
	v_and_b32_e32 v135, 0xffff0000, v111
	v_pk_add_f32 v[92:93], v[92:93], v[132:133]
	v_pk_add_f32 v[94:95], v[94:95], v[134:135]
	v_pk_mul_f32 v[136:137], v[80:81], v[80:81]
	v_pk_mul_f32 v[128:129], v[82:83], v[82:83]
	v_pk_fma_f32 v[136:137], v[84:85], v[84:85], v[136:137]
	v_pk_fma_f32 v[128:129], v[86:87], v[86:87], v[128:129]
	v_pk_fma_f32 v[136:137], v[88:89], v[88:89], v[136:137]
	v_pk_fma_f32 v[128:129], v[90:91], v[90:91], v[128:129]
	v_pk_fma_f32 v[136:137], v[92:93], v[92:93], v[136:137]
	v_pk_fma_f32 v[128:129], v[94:95], v[94:95], v[128:129]
	v_pk_add_f32 v[136:137], v[136:137], v[128:129]
	s_nop 0
	v_add_f32_e32 v136, v136, v137
	s_nop 1
	v_add_f32_dpp v136, v136, v136 quad_perm:[1,0,3,2] row_mask:0xf bank_mask:0xf
	s_nop 1
	v_add_f32_dpp v136, v136, v136 quad_perm:[2,3,0,1] row_mask:0xf bank_mask:0xf
	s_nop 1
	v_add_f32_dpp v136, v136, v136 row_half_mirror row_mask:0xf bank_mask:0xf
	s_nop 1
	v_add_f32_dpp v136, v136, v136 row_mirror row_mask:0xf bank_mask:0xf
	s_nop 1
	v_add_f32_dpp v136, v136, v136 row_bcast:15 row_mask:0xa bank_mask:0xf
	s_nop 1
	v_add_f32_dpp v136, v136, v136 row_bcast:31 row_mask:0xc bank_mask:0xf
	s_nop 1
	v_readlane_b32 s16, v136, 63
	s_nop 3
	v_fma_f32 v138, s16, v140, v141
	v_rsq_f32_e32 v138, v138
	s_nop 0
	v_mov_b32_e32 v139, v138
	v_pk_mul_f32 v[80:81], v[80:81], v[138:139]
	v_pk_mul_f32 v[82:83], v[82:83], v[138:139]
	v_pk_mul_f32 v[84:85], v[84:85], v[138:139]
	v_pk_mul_f32 v[86:87], v[86:87], v[138:139]
	v_pk_mul_f32 v[88:89], v[88:89], v[138:139]
	v_pk_mul_f32 v[90:91], v[90:91], v[138:139]
	v_pk_mul_f32 v[92:93], v[92:93], v[138:139]
	v_pk_mul_f32 v[94:95], v[94:95], v[138:139]
	v_pk_mul_f32 v[80:81], v[80:81], v[112:113]
	v_pk_mul_f32 v[82:83], v[82:83], v[114:115]
	v_pk_mul_f32 v[84:85], v[84:85], v[116:117]
	v_pk_mul_f32 v[86:87], v[86:87], v[118:119]
	v_pk_mul_f32 v[88:89], v[88:89], v[120:121]
	v_pk_mul_f32 v[90:91], v[90:91], v[122:123]
	v_pk_mul_f32 v[92:93], v[92:93], v[124:125]
	v_pk_mul_f32 v[94:95], v[94:95], v[126:127]
	global_store_dwordx4 v142, v[80:83], s[8:9]
	global_store_dwordx4 v142, v[84:87], s[8:9] offset:1024
	global_store_dwordx4 v142, v[88:91], s[8:9] offset:2048
	global_store_dwordx4 v142, v[92:95], s[8:9] offset:3072
	s_add_u32 s8, s8, s10
	s_addc_u32 s9, s9, 0
	s_branch .Lfnorm_loop
.Lfnorm_drain0:
	s_waitcnt vmcnt(12)
	v_lshlrev_b32_e32 v128, 16, v32
	v_and_b32_e32 v129, 0xffff0000, v32
	v_lshlrev_b32_e32 v130, 16, v33
	v_and_b32_e32 v131, 0xffff0000, v33
	v_pk_add_f32 v[16:17], v[16:17], v[128:129]
	v_pk_add_f32 v[18:19], v[18:19], v[130:131]
	v_lshlrev_b32_e32 v132, 16, v34
	v_and_b32_e32 v133, 0xffff0000, v34
	v_lshlrev_b32_e32 v134, 16, v35
	v_and_b32_e32 v135, 0xffff0000, v35
	v_pk_add_f32 v[20:21], v[20:21], v[132:133]
	v_pk_add_f32 v[22:23], v[22:23], v[134:135]
	v_lshlrev_b32_e32 v128, 16, v36
	v_and_b32_e32 v129, 0xffff0000, v36
	v_lshlrev_b32_e32 v130, 16, v37
	v_and_b32_e32 v131, 0xffff0000, v37
	v_pk_add_f32 v[24:25], v[24:25], v[128:129]
	v_pk_add_f32 v[26:27], v[26:27], v[130:131]
	v_lshlrev_b32_e32 v132, 16, v38
	v_and_b32_e32 v133, 0xffff0000, v38
	v_lshlrev_b32_e32 v134, 16, v39
	v_and_b32_e32 v135, 0xffff0000, v39
	v_pk_add_f32 v[28:29], v[28:29], v[132:133]
	v_pk_add_f32 v[30:31], v[30:31], v[134:135]
	v_lshlrev_b32_e32 v128, 16, v40
	v_and_b32_e32 v129, 0xffff0000, v40
	v_lshlrev_b32_e32 v130, 16, v41
	v_and_b32_e32 v131, 0xffff0000, v41
	v_pk_add_f32 v[16:17], v[16:17], v[128:129]
	v_pk_add_f32 v[18:19], v[18:19], v[130:131]
	v_lshlrev_b32_e32 v132, 16, v42
	v_and_b32_e32 v133, 0xffff0000, v42
	v_lshlrev_b32_e32 v134, 16, v43
	v_and_b32_e32 v135, 0xffff0000, v43
	v_pk_add_f32 v[20:21], v[20:21], v[132:133]
	v_pk_add_f32 v[22:23], v[22:23], v[134:135]
	v_lshlrev_b32_e32 v128, 16, v44
	v_and_b32_e32 v129, 0xffff0000, v44
	v_lshlrev_b32_e32 v130, 16, v45
	v_and_b32_e32 v131, 0xffff0000, v45
	v_pk_add_f32 v[24:25], v[24:25], v[128:129]
	v_pk_add_f32 v[26:27], v[26:27], v[130:131]
	v_lshlrev_b32_e32 v132, 16, v46
	v_and_b32_e32 v133, 0xffff0000, v46
	v_lshlrev_b32_e32 v134, 16, v47
	v_and_b32_e32 v135, 0xffff0000, v47
	v_pk_add_f32 v[28:29], v[28:29], v[132:133]
	v_pk_add_f32 v[30:31], v[30:31], v[134:135]
	v_pk_mul_f32 v[136:137], v[16:17], v[16:17]
	v_pk_mul_f32 v[128:129], v[18:19], v[18:19]
	v_pk_fma_f32 v[136:137], v[20:21], v[20:21], v[136:137]
	v_pk_fma_f32 v[128:129], v[22:23], v[22:23], v[128:129]
	v_pk_fma_f32 v[136:137], v[24:25], v[24:25], v[136:137]
	v_pk_fma_f32 v[128:129], v[26:27], v[26:27], v[128:129]
	v_pk_fma_f32 v[136:137], v[28:29], v[28:29], v[136:137]
	v_pk_fma_f32 v[128:129], v[30:31], v[30:31], v[128:129]
	v_pk_add_f32 v[136:137], v[136:137], v[128:129]
	s_nop 0
	v_add_f32_e32 v136, v136, v137
	s_nop 1
	v_add_f32_dpp v136, v136, v136 quad_perm:[1,0,3,2] row_mask:0xf bank_mask:0xf
	s_nop 1
	v_add_f32_dpp v136, v136, v136 quad_perm:[2,3,0,1] row_mask:0xf bank_mask:0xf
	s_nop 1
	v_add_f32_dpp v136, v136, v136 row_half_mirror row_mask:0xf bank_mask:0xf
	s_nop 1
	v_add_f32_dpp v136, v136, v136 row_mirror row_mask:0xf bank_mask:0xf
	s_nop 1
	v_add_f32_dpp v136, v136, v136 row_bcast:15 row_mask:0xa bank_mask:0xf
	s_nop 1
	v_add_f32_dpp v136, v136, v136 row_bcast:31 row_mask:0xc bank_mask:0xf
	s_nop 1
	v_readlane_b32 s16, v136, 63
	s_nop 3
	v_fma_f32 v138, s16, v140, v141
	v_rsq_f32_e32 v138, v138
	s_nop 0
	v_mov_b32_e32 v139, v138
	v_pk_mul_f32 v[16:17], v[16:17], v[138:139]
	v_pk_mul_f32 v[18:19], v[18:19], v[138:139]
	v_pk_mul_f32 v[20:21], v[20:21], v[138:139]
	v_pk_mul_f32 v[22:23], v[22:23], v[138:139]
	v_pk_mul_f32 v[24:25], v[24:25], v[138:139]
	v_pk_mul_f32 v[26:27], v[26:27], v[138:139]
	v_pk_mul_f32 v[28:29], v[28:29], v[138:139]
	v_pk_mul_f32 v[30:31], v[30:31], v[138:139]
	v_pk_mul_f32 v[16:17], v[16:17], v[112:113]
	v_pk_mul_f32 v[18:19], v[18:19], v[114:115]
	v_pk_mul_f32 v[20:21], v[20:21], v[116:117]
	v_pk_mul_f32 v[22:23], v[22:23], v[118:119]
	v_pk_mul_f32 v[24:25], v[24:25], v[120:121]
	v_pk_mul_f32 v[26:27], v[26:27], v[122:123]
	v_pk_mul_f32 v[28:29], v[28:29], v[124:125]
	v_pk_mul_f32 v[30:31], v[30:31], v[126:127]
	global_store_dwordx4 v142, v[16:19], s[8:9]
	global_store_dwordx4 v142, v[20:23], s[8:9] offset:1024
	global_store_dwordx4 v142, v[24:27], s[8:9] offset:2048
	global_store_dwordx4 v142, v[28:31], s[8:9] offset:3072
	s_add_u32 s8, s8, s10
	s_addc_u32 s9, s9, 0
	s_waitcnt vmcnt(4)
	v_lshlrev_b32_e32 v128, 16, v64
	v_and_b32_e32 v129, 0xffff0000, v64
	v_lshlrev_b32_e32 v130, 16, v65
	v_and_b32_e32 v131, 0xffff0000, v65
	v_pk_add_f32 v[48:49], v[48:49], v[128:129]
	v_pk_add_f32 v[50:51], v[50:51], v[130:131]
	v_lshlrev_b32_e32 v132, 16, v66
	v_and_b32_e32 v133, 0xffff0000, v66
	v_lshlrev_b32_e32 v134, 16, v67
	v_and_b32_e32 v135, 0xffff0000, v67
	v_pk_add_f32 v[52:53], v[52:53], v[132:133]
	v_pk_add_f32 v[54:55], v[54:55], v[134:135]
	v_lshlrev_b32_e32 v128, 16, v68
	v_and_b32_e32 v129, 0xffff0000, v68
	v_lshlrev_b32_e32 v130, 16, v69
	v_and_b32_e32 v131, 0xffff0000, v69
	v_pk_add_f32 v[56:57], v[56:57], v[128:129]
	v_pk_add_f32 v[58:59], v[58:59], v[130:131]
	v_lshlrev_b32_e32 v132, 16, v70
	v_and_b32_e32 v133, 0xffff0000, v70
	v_lshlrev_b32_e32 v134, 16, v71
	v_and_b32_e32 v135, 0xffff0000, v71
	v_pk_add_f32 v[60:61], v[60:61], v[132:133]
	v_pk_add_f32 v[62:63], v[62:63], v[134:135]
	v_lshlrev_b32_e32 v128, 16, v72
	v_and_b32_e32 v129, 0xffff0000, v72
	v_lshlrev_b32_e32 v130, 16, v73
	v_and_b32_e32 v131, 0xffff0000, v73
	v_pk_add_f32 v[48:49], v[48:49], v[128:129]
	v_pk_add_f32 v[50:51], v[50:51], v[130:131]
	v_lshlrev_b32_e32 v132, 16, v74
	v_and_b32_e32 v133, 0xffff0000, v74
	v_lshlrev_b32_e32 v134, 16, v75
	v_and_b32_e32 v135, 0xffff0000, v75
	v_pk_add_f32 v[52:53], v[52:53], v[132:133]
	v_pk_add_f32 v[54:55], v[54:55], v[134:135]
	v_lshlrev_b32_e32 v128, 16, v76
	v_and_b32_e32 v129, 0xffff0000, v76
	v_lshlrev_b32_e32 v130, 16, v77
	v_and_b32_e32 v131, 0xffff0000, v77
	v_pk_add_f32 v[56:57], v[56:57], v[128:129]
	v_pk_add_f32 v[58:59], v[58:59], v[130:131]
	v_lshlrev_b32_e32 v132, 16, v78
	v_and_b32_e32 v133, 0xffff0000, v78
	v_lshlrev_b32_e32 v134, 16, v79
	v_and_b32_e32 v135, 0xffff0000, v79
	v_pk_add_f32 v[60:61], v[60:61], v[132:133]
	v_pk_add_f32 v[62:63], v[62:63], v[134:135]
	v_pk_mul_f32 v[136:137], v[48:49], v[48:49]
	v_pk_mul_f32 v[128:129], v[50:51], v[50:51]
	v_pk_fma_f32 v[136:137], v[52:53], v[52:53], v[136:137]
	v_pk_fma_f32 v[128:129], v[54:55], v[54:55], v[128:129]
	v_pk_fma_f32 v[136:137], v[56:57], v[56:57], v[136:137]
	v_pk_fma_f32 v[128:129], v[58:59], v[58:59], v[128:129]
	v_pk_fma_f32 v[136:137], v[60:61], v[60:61], v[136:137]
	v_pk_fma_f32 v[128:129], v[62:63], v[62:63], v[128:129]
	v_pk_add_f32 v[136:137], v[136:137], v[128:129]
	s_nop 0
	v_add_f32_e32 v136, v136, v137
	s_nop 1
	v_add_f32_dpp v136, v136, v136 quad_perm:[1,0,3,2] row_mask:0xf bank_mask:0xf
	s_nop 1
	v_add_f32_dpp v136, v136, v136 quad_perm:[2,3,0,1] row_mask:0xf bank_mask:0xf
	s_nop 1
	v_add_f32_dpp v136, v136, v136 row_half_mirror row_mask:0xf bank_mask:0xf
	s_nop 1
	v_add_f32_dpp v136, v136, v136 row_mirror row_mask:0xf bank_mask:0xf
	s_nop 1
	v_add_f32_dpp v136, v136, v136 row_bcast:15 row_mask:0xa bank_mask:0xf
	s_nop 1
	v_add_f32_dpp v136, v136, v136 row_bcast:31 row_mask:0xc bank_mask:0xf
	s_nop 1
	v_readlane_b32 s16, v136, 63
	s_nop 3
	v_fma_f32 v138, s16, v140, v141
	v_rsq_f32_e32 v138, v138
	s_nop 0
	v_mov_b32_e32 v139, v138
	v_pk_mul_f32 v[48:49], v[48:49], v[138:139]
	v_pk_mul_f32 v[50:51], v[50:51], v[138:139]
	v_pk_mul_f32 v[52:53], v[52:53], v[138:139]
	v_pk_mul_f32 v[54:55], v[54:55], v[138:139]
	v_pk_mul_f32 v[56:57], v[56:57], v[138:139]
	v_pk_mul_f32 v[58:59], v[58:59], v[138:139]
	v_pk_mul_f32 v[60:61], v[60:61], v[138:139]
	v_pk_mul_f32 v[62:63], v[62:63], v[138:139]
	v_pk_mul_f32 v[48:49], v[48:49], v[112:113]
	v_pk_mul_f32 v[50:51], v[50:51], v[114:115]
	v_pk_mul_f32 v[52:53], v[52:53], v[116:117]
	v_pk_mul_f32 v[54:55], v[54:55], v[118:119]
	v_pk_mul_f32 v[56:57], v[56:57], v[120:121]
	v_pk_mul_f32 v[58:59], v[58:59], v[122:123]
	v_pk_mul_f32 v[60:61], v[60:61], v[124:125]
	v_pk_mul_f32 v[62:63], v[62:63], v[126:127]
	global_store_dwordx4 v142, v[48:51], s[8:9]
	global_store_dwordx4 v142, v[52:55], s[8:9] offset:1024
	global_store_dwordx4 v142, v[56:59], s[8:9] offset:2048
	global_store_dwordx4 v142, v[60:63], s[8:9] offset:3072
	s_add_u32 s8, s8, s10
	s_addc_u32 s9, s9, 0
	s_branch .Lfnorm_done
.Lfnorm_drain1:
	s_waitcnt vmcnt(12)
	v_lshlrev_b32_e32 v128, 16, v64
	v_and_b32_e32 v129, 0xffff0000, v64
	v_lshlrev_b32_e32 v130, 16, v65
	v_and_b32_e32 v131, 0xffff0000, v65
	v_pk_add_f32 v[48:49], v[48:49], v[128:129]
	v_pk_add_f32 v[50:51], v[50:51], v[130:131]
	v_lshlrev_b32_e32 v132, 16, v66
	v_and_b32_e32 v133, 0xffff0000, v66
	v_lshlrev_b32_e32 v134, 16, v67
	v_and_b32_e32 v135, 0xffff0000, v67
	v_pk_add_f32 v[52:53], v[52:53], v[132:133]
	v_pk_add_f32 v[54:55], v[54:55], v[134:135]
	v_lshlrev_b32_e32 v128, 16, v68
	v_and_b32_e32 v129, 0xffff0000, v68
	v_lshlrev_b32_e32 v130, 16, v69
	v_and_b32_e32 v131, 0xffff0000, v69
	v_pk_add_f32 v[56:57], v[56:57], v[128:129]
	v_pk_add_f32 v[58:59], v[58:59], v[130:131]
	v_lshlrev_b32_e32 v132, 16, v70
	v_and_b32_e32 v133, 0xffff0000, v70
	v_lshlrev_b32_e32 v134, 16, v71
	v_and_b32_e32 v135, 0xffff0000, v71
	v_pk_add_f32 v[60:61], v[60:61], v[132:133]
	v_pk_add_f32 v[62:63], v[62:63], v[134:135]
	v_lshlrev_b32_e32 v128, 16, v72
	v_and_b32_e32 v129, 0xffff0000, v72
	v_lshlrev_b32_e32 v130, 16, v73
	v_and_b32_e32 v131, 0xffff0000, v73
	v_pk_add_f32 v[48:49], v[48:49], v[128:129]
	v_pk_add_f32 v[50:51], v[50:51], v[130:131]
	v_lshlrev_b32_e32 v132, 16, v74
	v_and_b32_e32 v133, 0xffff0000, v74
	v_lshlrev_b32_e32 v134, 16, v75
	v_and_b32_e32 v135, 0xffff0000, v75
	v_pk_add_f32 v[52:53], v[52:53], v[132:133]
	v_pk_add_f32 v[54:55], v[54:55], v[134:135]
	v_lshlrev_b32_e32 v128, 16, v76
	v_and_b32_e32 v129, 0xffff0000, v76
	v_lshlrev_b32_e32 v130, 16, v77
	v_and_b32_e32 v131, 0xffff0000, v77
	v_pk_add_f32 v[56:57], v[56:57], v[128:129]
	v_pk_add_f32 v[58:59], v[58:59], v[130:131]
	v_lshlrev_b32_e32 v132, 16, v78
	v_and_b32_e32 v133, 0xffff0000, v78
	v_lshlrev_b32_e32 v134, 16, v79
	v_and_b32_e32 v135, 0xffff0000, v79
	v_pk_add_f32 v[60:61], v[60:61], v[132:133]
	v_pk_add_f32 v[62:63], v[62:63], v[134:135]
	v_pk_mul_f32 v[136:137], v[48:49], v[48:49]
	v_pk_mul_f32 v[128:129], v[50:51], v[50:51]
	v_pk_fma_f32 v[136:137], v[52:53], v[52:53], v[136:137]
	v_pk_fma_f32 v[128:129], v[54:55], v[54:55], v[128:129]
	v_pk_fma_f32 v[136:137], v[56:57], v[56:57], v[136:137]
	v_pk_fma_f32 v[128:129], v[58:59], v[58:59], v[128:129]
	v_pk_fma_f32 v[136:137], v[60:61], v[60:61], v[136:137]
	v_pk_fma_f32 v[128:129], v[62:63], v[62:63], v[128:129]
	v_pk_add_f32 v[136:137], v[136:137], v[128:129]
	s_nop 0
	v_add_f32_e32 v136, v136, v137
	s_nop 1
	v_add_f32_dpp v136, v136, v136 quad_perm:[1,0,3,2] row_mask:0xf bank_mask:0xf
	s_nop 1
	v_add_f32_dpp v136, v136, v136 quad_perm:[2,3,0,1] row_mask:0xf bank_mask:0xf
	s_nop 1
	v_add_f32_dpp v136, v136, v136 row_half_mirror row_mask:0xf bank_mask:0xf
	s_nop 1
	v_add_f32_dpp v136, v136, v136 row_mirror row_mask:0xf bank_mask:0xf
	s_nop 1
	v_add_f32_dpp v136, v136, v136 row_bcast:15 row_mask:0xa bank_mask:0xf
	s_nop 1
	v_add_f32_dpp v136, v136, v136 row_bcast:31 row_mask:0xc bank_mask:0xf
	s_nop 1
	v_readlane_b32 s16, v136, 63
	s_nop 3
	v_fma_f32 v138, s16, v140, v141
	v_rsq_f32_e32 v138, v138
	s_nop 0
	v_mov_b32_e32 v139, v138
	v_pk_mul_f32 v[48:49], v[48:49], v[138:139]
	v_pk_mul_f32 v[50:51], v[50:51], v[138:139]
	v_pk_mul_f32 v[52:53], v[52:53], v[138:139]
	v_pk_mul_f32 v[54:55], v[54:55], v[138:139]
	v_pk_mul_f32 v[56:57], v[56:57], v[138:139]
	v_pk_mul_f32 v[58:59], v[58:59], v[138:139]
	v_pk_mul_f32 v[60:61], v[60:61], v[138:139]
	v_pk_mul_f32 v[62:63], v[62:63], v[138:139]
	v_pk_mul_f32 v[48:49], v[48:49], v[112:113]
	v_pk_mul_f32 v[50:51], v[50:51], v[114:115]
	v_pk_mul_f32 v[52:53], v[52:53], v[116:117]
	v_pk_mul_f32 v[54:55], v[54:55], v[118:119]
	v_pk_mul_f32 v[56:57], v[56:57], v[120:121]
	v_pk_mul_f32 v[58:59], v[58:59], v[122:123]
	v_pk_mul_f32 v[60:61], v[60:61], v[124:125]
	v_pk_mul_f32 v[62:63], v[62:63], v[126:127]
	global_store_dwordx4 v142, v[48:51], s[8:9]
	global_store_dwordx4 v142, v[52:55], s[8:9] offset:1024
	global_store_dwordx4 v142, v[56:59], s[8:9] offset:2048
	global_store_dwordx4 v142, v[60:63], s[8:9] offset:3072
	s_add_u32 s8, s8, s10
	s_addc_u32 s9, s9, 0
	s_waitcnt vmcnt(4)
	v_lshlrev_b32_e32 v128, 16, v96
	v_and_b32_e32 v129, 0xffff0000, v96
	v_lshlrev_b32_e32 v130, 16, v97
	v_and_b32_e32 v131, 0xffff0000, v97
	v_pk_add_f32 v[80:81], v[80:81], v[128:129]
	v_pk_add_f32 v[82:83], v[82:83], v[130:131]
	v_lshlrev_b32_e32 v132, 16, v98
	v_and_b32_e32 v133, 0xffff0000, v98
	v_lshlrev_b32_e32 v134, 16, v99
	v_and_b32_e32 v135, 0xffff0000, v99
	v_pk_add_f32 v[84:85], v[84:85], v[132:133]
	v_pk_add_f32 v[86:87], v[86:87], v[134:135]
	v_lshlrev_b32_e32 v128, 16, v100
	v_and_b32_e32 v129, 0xffff0000, v100
	v_lshlrev_b32_e32 v130, 16, v101
	v_and_b32_e32 v131, 0xffff0000, v101
	v_pk_add_f32 v[88:89], v[88:89], v[128:129]
	v_pk_add_f32 v[90:91], v[90:91], v[130:131]
	v_lshlrev_b32_e32 v132, 16, v102
	v_and_b32_e32 v133, 0xffff0000, v102
	v_lshlrev_b32_e32 v134, 16, v103
	v_and_b32_e32 v135, 0xffff0000, v103
	v_pk_add_f32 v[92:93], v[92:93], v[132:133]
	v_pk_add_f32 v[94:95], v[94:95], v[134:135]
	v_lshlrev_b32_e32 v128, 16, v104
	v_and_b32_e32 v129, 0xffff0000, v104
	v_lshlrev_b32_e32 v130, 16, v105
	v_and_b32_e32 v131, 0xffff0000, v105
	v_pk_add_f32 v[80:81], v[80:81], v[128:129]
	v_pk_add_f32 v[82:83], v[82:83], v[130:131]
	v_lshlrev_b32_e32 v132, 16, v106
	v_and_b32_e32 v133, 0xffff0000, v106
	v_lshlrev_b32_e32 v134, 16, v107
	v_and_b32_e32 v135, 0xffff0000, v107
	v_pk_add_f32 v[84:85], v[84:85], v[132:133]
	v_pk_add_f32 v[86:87], v[86:87], v[134:135]
	v_lshlrev_b32_e32 v128, 16, v108
	v_and_b32_e32 v129, 0xffff0000, v108
	v_lshlrev_b32_e32 v130, 16, v109
	v_and_b32_e32 v131, 0xffff0000, v109
	v_pk_add_f32 v[88:89], v[88:89], v[128:129]
	v_pk_add_f32 v[90:91], v[90:91], v[130:131]
	v_lshlrev_b32_e32 v132, 16, v110
	v_and_b32_e32 v133, 0xffff0000, v110
	v_lshlrev_b32_e32 v134, 16, v111
	v_and_b32_e32 v135, 0xffff0000, v111
	v_pk_add_f32 v[92:93], v[92:93], v[132:133]
	v_pk_add_f32 v[94:95], v[94:95], v[134:135]
	v_pk_mul_f32 v[136:137], v[80:81], v[80:81]
	v_pk_mul_f32 v[128:129], v[82:83], v[82:83]
	v_pk_fma_f32 v[136:137], v[84:85], v[84:85], v[136:137]
	v_pk_fma_f32 v[128:129], v[86:87], v[86:87], v[128:129]
	v_pk_fma_f32 v[136:137], v[88:89], v[88:89], v[136:137]
	v_pk_fma_f32 v[128:129], v[90:91], v[90:91], v[128:129]
	v_pk_fma_f32 v[136:137], v[92:93], v[92:93], v[136:137]
	v_pk_fma_f32 v[128:129], v[94:95], v[94:95], v[128:129]
	v_pk_add_f32 v[136:137], v[136:137], v[128:129]
	s_nop 0
	v_add_f32_e32 v136, v136, v137
	s_nop 1
	v_add_f32_dpp v136, v136, v136 quad_perm:[1,0,3,2] row_mask:0xf bank_mask:0xf
	s_nop 1
	v_add_f32_dpp v136, v136, v136 quad_perm:[2,3,0,1] row_mask:0xf bank_mask:0xf
	s_nop 1
	v_add_f32_dpp v136, v136, v136 row_half_mirror row_mask:0xf bank_mask:0xf
	s_nop 1
	v_add_f32_dpp v136, v136, v136 row_mirror row_mask:0xf bank_mask:0xf
	s_nop 1
	v_add_f32_dpp v136, v136, v136 row_bcast:15 row_mask:0xa bank_mask:0xf
	s_nop 1
	v_add_f32_dpp v136, v136, v136 row_bcast:31 row_mask:0xc bank_mask:0xf
	s_nop 1
	v_readlane_b32 s16, v136, 63
	s_nop 3
	v_fma_f32 v138, s16, v140, v141
	v_rsq_f32_e32 v138, v138
	s_nop 0
	v_mov_b32_e32 v139, v138
	v_pk_mul_f32 v[80:81], v[80:81], v[138:139]
	v_pk_mul_f32 v[82:83], v[82:83], v[138:139]
	v_pk_mul_f32 v[84:85], v[84:85], v[138:139]
	v_pk_mul_f32 v[86:87], v[86:87], v[138:139]
	v_pk_mul_f32 v[88:89], v[88:89], v[138:139]
	v_pk_mul_f32 v[90:91], v[90:91], v[138:139]
	v_pk_mul_f32 v[92:93], v[92:93], v[138:139]
	v_pk_mul_f32 v[94:95], v[94:95], v[138:139]
	v_pk_mul_f32 v[80:81], v[80:81], v[112:113]
	v_pk_mul_f32 v[82:83], v[82:83], v[114:115]
	v_pk_mul_f32 v[84:85], v[84:85], v[116:117]
	v_pk_mul_f32 v[86:87], v[86:87], v[118:119]
	v_pk_mul_f32 v[88:89], v[88:89], v[120:121]
	v_pk_mul_f32 v[90:91], v[90:91], v[122:123]
	v_pk_mul_f32 v[92:93], v[92:93], v[124:125]
	v_pk_mul_f32 v[94:95], v[94:95], v[126:127]
	global_store_dwordx4 v142, v[80:83], s[8:9]
	global_store_dwordx4 v142, v[84:87], s[8:9] offset:1024
	global_store_dwordx4 v142, v[88:91], s[8:9] offset:2048
	global_store_dwordx4 v142, v[92:95], s[8:9] offset:3072
	s_add_u32 s8, s8, s10
	s_addc_u32 s9, s9, 0
	s_branch .Lfnorm_done
.Lfnorm_drain2:
	s_waitcnt vmcnt(12)
	v_lshlrev_b32_e32 v128, 16, v96
	v_and_b32_e32 v129, 0xffff0000, v96
	v_lshlrev_b32_e32 v130, 16, v97
	v_and_b32_e32 v131, 0xffff0000, v97
	v_pk_add_f32 v[80:81], v[80:81], v[128:129]
	v_pk_add_f32 v[82:83], v[82:83], v[130:131]
	v_lshlrev_b32_e32 v132, 16, v98
	v_and_b32_e32 v133, 0xffff0000, v98
	v_lshlrev_b32_e32 v134, 16, v99
	v_and_b32_e32 v135, 0xffff0000, v99
	v_pk_add_f32 v[84:85], v[84:85], v[132:133]
	v_pk_add_f32 v[86:87], v[86:87], v[134:135]
	v_lshlrev_b32_e32 v128, 16, v100
	v_and_b32_e32 v129, 0xffff0000, v100
	v_lshlrev_b32_e32 v130, 16, v101
	v_and_b32_e32 v131, 0xffff0000, v101
	v_pk_add_f32 v[88:89], v[88:89], v[128:129]
	v_pk_add_f32 v[90:91], v[90:91], v[130:131]
	v_lshlrev_b32_e32 v132, 16, v102
	v_and_b32_e32 v133, 0xffff0000, v102
	v_lshlrev_b32_e32 v134, 16, v103
	v_and_b32_e32 v135, 0xffff0000, v103
	v_pk_add_f32 v[92:93], v[92:93], v[132:133]
	v_pk_add_f32 v[94:95], v[94:95], v[134:135]
	v_lshlrev_b32_e32 v128, 16, v104
	v_and_b32_e32 v129, 0xffff0000, v104
	v_lshlrev_b32_e32 v130, 16, v105
	v_and_b32_e32 v131, 0xffff0000, v105
	v_pk_add_f32 v[80:81], v[80:81], v[128:129]
	v_pk_add_f32 v[82:83], v[82:83], v[130:131]
	v_lshlrev_b32_e32 v132, 16, v106
	v_and_b32_e32 v133, 0xffff0000, v106
	v_lshlrev_b32_e32 v134, 16, v107
	v_and_b32_e32 v135, 0xffff0000, v107
	v_pk_add_f32 v[84:85], v[84:85], v[132:133]
	v_pk_add_f32 v[86:87], v[86:87], v[134:135]
	v_lshlrev_b32_e32 v128, 16, v108
	v_and_b32_e32 v129, 0xffff0000, v108
	v_lshlrev_b32_e32 v130, 16, v109
	v_and_b32_e32 v131, 0xffff0000, v109
	v_pk_add_f32 v[88:89], v[88:89], v[128:129]
	v_pk_add_f32 v[90:91], v[90:91], v[130:131]
	v_lshlrev_b32_e32 v132, 16, v110
	v_and_b32_e32 v133, 0xffff0000, v110
	v_lshlrev_b32_e32 v134, 16, v111
	v_and_b32_e32 v135, 0xffff0000, v111
	v_pk_add_f32 v[92:93], v[92:93], v[132:133]
	v_pk_add_f32 v[94:95], v[94:95], v[134:135]
	v_pk_mul_f32 v[136:137], v[80:81], v[80:81]
	v_pk_mul_f32 v[128:129], v[82:83], v[82:83]
	v_pk_fma_f32 v[136:137], v[84:85], v[84:85], v[136:137]
	v_pk_fma_f32 v[128:129], v[86:87], v[86:87], v[128:129]
	v_pk_fma_f32 v[136:137], v[88:89], v[88:89], v[136:137]
	v_pk_fma_f32 v[128:129], v[90:91], v[90:91], v[128:129]
	v_pk_fma_f32 v[136:137], v[92:93], v[92:93], v[136:137]
	v_pk_fma_f32 v[128:129], v[94:95], v[94:95], v[128:129]
	v_pk_add_f32 v[136:137], v[136:137], v[128:129]
	s_nop 0
	v_add_f32_e32 v136, v136, v137
	s_nop 1
	v_add_f32_dpp v136, v136, v136 quad_perm:[1,0,3,2] row_mask:0xf bank_mask:0xf
	s_nop 1
	v_add_f32_dpp v136, v136, v136 quad_perm:[2,3,0,1] row_mask:0xf bank_mask:0xf
	s_nop 1
	v_add_f32_dpp v136, v136, v136 row_half_mirror row_mask:0xf bank_mask:0xf
	s_nop 1
	v_add_f32_dpp v136, v136, v136 row_mirror row_mask:0xf bank_mask:0xf
	s_nop 1
	v_add_f32_dpp v136, v136, v136 row_bcast:15 row_mask:0xa bank_mask:0xf
	s_nop 1
	v_add_f32_dpp v136, v136, v136 row_bcast:31 row_mask:0xc bank_mask:0xf
	s_nop 1
	v_readlane_b32 s16, v136, 63
	s_nop 3
	v_fma_f32 v138, s16, v140, v141
	v_rsq_f32_e32 v138, v138
	s_nop 0
	v_mov_b32_e32 v139, v138
	v_pk_mul_f32 v[80:81], v[80:81], v[138:139]
	v_pk_mul_f32 v[82:83], v[82:83], v[138:139]
	v_pk_mul_f32 v[84:85], v[84:85], v[138:139]
	v_pk_mul_f32 v[86:87], v[86:87], v[138:139]
	v_pk_mul_f32 v[88:89], v[88:89], v[138:139]
	v_pk_mul_f32 v[90:91], v[90:91], v[138:139]
	v_pk_mul_f32 v[92:93], v[92:93], v[138:139]
	v_pk_mul_f32 v[94:95], v[94:95], v[138:139]
	v_pk_mul_f32 v[80:81], v[80:81], v[112:113]
	v_pk_mul_f32 v[82:83], v[82:83], v[114:115]
	v_pk_mul_f32 v[84:85], v[84:85], v[116:117]
	v_pk_mul_f32 v[86:87], v[86:87], v[118:119]
	v_pk_mul_f32 v[88:89], v[88:89], v[120:121]
	v_pk_mul_f32 v[90:91], v[90:91], v[122:123]
	v_pk_mul_f32 v[92:93], v[92:93], v[124:125]
	v_pk_mul_f32 v[94:95], v[94:95], v[126:127]
	global_store_dwordx4 v142, v[80:83], s[8:9]
	global_store_dwordx4 v142, v[84:87], s[8:9] offset:1024
	global_store_dwordx4 v142, v[88:91], s[8:9] offset:2048
	global_store_dwordx4 v142, v[92:95], s[8:9] offset:3072
	s_add_u32 s8, s8, s10
	s_addc_u32 s9, s9, 0
	s_waitcnt vmcnt(4)
	v_lshlrev_b32_e32 v128, 16, v32
	v_and_b32_e32 v129, 0xffff0000, v32
	v_lshlrev_b32_e32 v130, 16, v33
	v_and_b32_e32 v131, 0xffff0000, v33
	v_pk_add_f32 v[16:17], v[16:17], v[128:129]
	v_pk_add_f32 v[18:19], v[18:19], v[130:131]
	v_lshlrev_b32_e32 v132, 16, v34
	v_and_b32_e32 v133, 0xffff0000, v34
	v_lshlrev_b32_e32 v134, 16, v35
	v_and_b32_e32 v135, 0xffff0000, v35
	v_pk_add_f32 v[20:21], v[20:21], v[132:133]
	v_pk_add_f32 v[22:23], v[22:23], v[134:135]
	v_lshlrev_b32_e32 v128, 16, v36
	v_and_b32_e32 v129, 0xffff0000, v36
	v_lshlrev_b32_e32 v130, 16, v37
	v_and_b32_e32 v131, 0xffff0000, v37
	v_pk_add_f32 v[24:25], v[24:25], v[128:129]
	v_pk_add_f32 v[26:27], v[26:27], v[130:131]
	v_lshlrev_b32_e32 v132, 16, v38
	v_and_b32_e32 v133, 0xffff0000, v38
	v_lshlrev_b32_e32 v134, 16, v39
	v_and_b32_e32 v135, 0xffff0000, v39
	v_pk_add_f32 v[28:29], v[28:29], v[132:133]
	v_pk_add_f32 v[30:31], v[30:31], v[134:135]
	v_lshlrev_b32_e32 v128, 16, v40
	v_and_b32_e32 v129, 0xffff0000, v40
	v_lshlrev_b32_e32 v130, 16, v41
	v_and_b32_e32 v131, 0xffff0000, v41
	v_pk_add_f32 v[16:17], v[16:17], v[128:129]
	v_pk_add_f32 v[18:19], v[18:19], v[130:131]
	v_lshlrev_b32_e32 v132, 16, v42
	v_and_b32_e32 v133, 0xffff0000, v42
	v_lshlrev_b32_e32 v134, 16, v43
	v_and_b32_e32 v135, 0xffff0000, v43
	v_pk_add_f32 v[20:21], v[20:21], v[132:133]
	v_pk_add_f32 v[22:23], v[22:23], v[134:135]
	v_lshlrev_b32_e32 v128, 16, v44
	v_and_b32_e32 v129, 0xffff0000, v44
	v_lshlrev_b32_e32 v130, 16, v45
	v_and_b32_e32 v131, 0xffff0000, v45
	v_pk_add_f32 v[24:25], v[24:25], v[128:129]
	v_pk_add_f32 v[26:27], v[26:27], v[130:131]
	v_lshlrev_b32_e32 v132, 16, v46
	v_and_b32_e32 v133, 0xffff0000, v46
	v_lshlrev_b32_e32 v134, 16, v47
	v_and_b32_e32 v135, 0xffff0000, v47
	v_pk_add_f32 v[28:29], v[28:29], v[132:133]
	v_pk_add_f32 v[30:31], v[30:31], v[134:135]
	v_pk_mul_f32 v[136:137], v[16:17], v[16:17]
	v_pk_mul_f32 v[128:129], v[18:19], v[18:19]
	v_pk_fma_f32 v[136:137], v[20:21], v[20:21], v[136:137]
	v_pk_fma_f32 v[128:129], v[22:23], v[22:23], v[128:129]
	v_pk_fma_f32 v[136:137], v[24:25], v[24:25], v[136:137]
	v_pk_fma_f32 v[128:129], v[26:27], v[26:27], v[128:129]
	v_pk_fma_f32 v[136:137], v[28:29], v[28:29], v[136:137]
	v_pk_fma_f32 v[128:129], v[30:31], v[30:31], v[128:129]
	v_pk_add_f32 v[136:137], v[136:137], v[128:129]
	s_nop 0
	v_add_f32_e32 v136, v136, v137
	s_nop 1
	v_add_f32_dpp v136, v136, v136 quad_perm:[1,0,3,2] row_mask:0xf bank_mask:0xf
	s_nop 1
	v_add_f32_dpp v136, v136, v136 quad_perm:[2,3,0,1] row_mask:0xf bank_mask:0xf
	s_nop 1
	v_add_f32_dpp v136, v136, v136 row_half_mirror row_mask:0xf bank_mask:0xf
	s_nop 1
	v_add_f32_dpp v136, v136, v136 row_mirror row_mask:0xf bank_mask:0xf
	s_nop 1
	v_add_f32_dpp v136, v136, v136 row_bcast:15 row_mask:0xa bank_mask:0xf
	s_nop 1
	v_add_f32_dpp v136, v136, v136 row_bcast:31 row_mask:0xc bank_mask:0xf
	s_nop 1
	v_readlane_b32 s16, v136, 63
	s_nop 3
	v_fma_f32 v138, s16, v140, v141
	v_rsq_f32_e32 v138, v138
	s_nop 0
	v_mov_b32_e32 v139, v138
	v_pk_mul_f32 v[16:17], v[16:17], v[138:139]
	v_pk_mul_f32 v[18:19], v[18:19], v[138:139]
	v_pk_mul_f32 v[20:21], v[20:21], v[138:139]
	v_pk_mul_f32 v[22:23], v[22:23], v[138:139]
	v_pk_mul_f32 v[24:25], v[24:25], v[138:139]
	v_pk_mul_f32 v[26:27], v[26:27], v[138:139]
	v_pk_mul_f32 v[28:29], v[28:29], v[138:139]
	v_pk_mul_f32 v[30:31], v[30:31], v[138:139]
	v_pk_mul_f32 v[16:17], v[16:17], v[112:113]
	v_pk_mul_f32 v[18:19], v[18:19], v[114:115]
	v_pk_mul_f32 v[20:21], v[20:21], v[116:117]
	v_pk_mul_f32 v[22:23], v[22:23], v[118:119]
	v_pk_mul_f32 v[24:25], v[24:25], v[120:121]
	v_pk_mul_f32 v[26:27], v[26:27], v[122:123]
	v_pk_mul_f32 v[28:29], v[28:29], v[124:125]
	v_pk_mul_f32 v[30:31], v[30:31], v[126:127]
	global_store_dwordx4 v142, v[16:19], s[8:9]
	global_store_dwordx4 v142, v[20:23], s[8:9] offset:1024
	global_store_dwordx4 v142, v[24:27], s[8:9] offset:2048
	global_store_dwordx4 v142, v[28:31], s[8:9] offset:3072
	s_add_u32 s8, s8, s10
	s_addc_u32 s9, s9, 0
.Lfnorm_done:
.LBB0_1465:
	s_or_b64 exec, exec, s[4:5]
	s_cmp_lt_i32 s23, 11
	s_cbranch_scc1 .LBB0_1477
	v_lshrrev_b32_e32 v1, 20, v0
	v_lshrrev_b32_e32 v0, 10, v0
	v_or_b32_e32 v0, v0, v1
	s_movk_i32 s0, 0x3ff
	v_and_or_b32 v0, v0, s0, v208
	v_cmp_eq_u32_e32 vcc, 0, v0
	s_waitcnt vmcnt(0) lgkmcnt(0)
	s_barrier
	s_and_saveexec_b64 s[0:1], vcc
	s_cbranch_execz .LBB0_1476
	v_readlane_b32 s2, v247, 9
	v_readlane_b32 s3, v247, 10
	buffer_wbl2 sc1
	s_load_dwordx2 s[2:3], s[2:3], 0x58
	v_mov_b32_e32 v2, 0
	s_mov_b64 s[4:5], exec
	v_mbcnt_lo_u32_b32 v1, s4, 0
	v_mbcnt_hi_u32_b32 v1, s5, v1
	s_waitcnt lgkmcnt(0)
	global_load_dword v0, v2, s[2:3] offset:40
	v_cmp_eq_u32_e32 vcc, 0, v1
	s_and_saveexec_b64 s[6:7], vcc
	s_cbranch_execz .LBB0_1469
	s_bcnt1_i32_b64 s4, s[4:5]
	v_mov_b32_e32 v3, s4
	global_atomic_add v3, v2, v3, s[2:3] offset:32 sc0
